# MoBA softmax: non-diagonal tiles with partially selected queries take the unmasked path with a per-lane 0/-inf bias folded into the scale FMA instead of the per-element masked path
# speedup vs baseline: 1.0071x; 1.0068x over previous
; __device__ void moba_item(const P& p, int bh, int qt, char* smem) {
;     ...
;     const int blk = tt >> 2;
;     const bool own = (blk == qblk);
;     const bool rowvalid = own || ((mymask >> blk) & 1u);
;     if (__any(rowvalid)) {
;       const int key0 = tt * 64;
;       f32x4 sacc[2][2];
; #pragma unroll
;       for (int st = 0; st < 2; ++st)
; #pragma unroll
;         for (int kt = 0; kt < 2; ++kt) {
;           sacc[st][kt] = (f32x4){0.f, 0.f, 0.f, 0.f};
;           const int row = 32 * st + 8 * (li >> 2) + 4 * kt + (li & 3);
; #pragma unroll
;           for (int kk = 0; kk < 4; ++kk) {
;             const bf16x8 kf = *(const bf16x8*)(sK + row * 256 + (((kk * 4 + g) ^ li) << 4));
;             sacc[st][kt] = __builtin_amdgcn_mfma_f32_16x16x32_bf16(kf, qf[kk], sacc[st][kt], 0, 0, 0);
;           }
;         }
;       const bool diag = (tt == ntiles - 1);
;       float mx = -INFINITY;
;       if (diag || !__all(rowvalid)) {
; #pragma unroll
;         for (int st = 0; st < 2; ++st)
; #pragma unroll
;           for (int kt = 0; kt < 2; ++kt)
; #pragma unroll
;             for (int r = 0; r < 4; ++r) {
;               const int key = key0 + 32 * st + 8 * g + 4 * kt + r;
;               bool ok = rowvalid && (!diag || key <= qpos);
;               const float sv = ok ? sacc[st][kt][r] * SC : -INFINITY;
;               sacc[st][kt][r] = sv;
;               mx = fmaxf(mx, sv);
;             }
;       } else {
; #pragma unroll
;         for (int st = 0; st < 2; ++st)
; #pragma unroll
;           for (int kt = 0; kt < 2; ++kt) {
;             sacc[st][kt] *= SC;
;             mx = fmaxf(mx, fmaxf(fmaxf(sacc[st][kt][0], sacc[st][kt][1]), fmaxf(sacc[st][kt][2], sacc[st][kt][3])));
;           }
;       }
.Lmoba_skipA:
.LBB0_616:
	s_lshr_b32 s6, s27, 2
	s_cmp_eq_u32 s6, s41
	s_cselect_b64 s[0:1], -1, 0
	s_lshl_b32 s6, 1, s6
	v_and_b32_e32 v0, s6, v149
	v_cmp_ne_u32_e32 vcc, 0, v0
	s_or_b64 s[6:7], s[0:1], vcc
	s_mov_b64 vcc, s[6:7]
	s_cbranch_vccz .LBB0_625
	v_add_u32_e32 v0, v155, v151
	v_add_u32_e32 v2, v155, v178
	v_add_u32_e32 v3, v155, v179
	v_add_u32_e32 v168, v155, v180
	s_cmp_eq_u32 s40, s27
	s_cselect_b64 s[0:1], -1, 0
	s_and_b64 vcc, exec, s[0:1]
	s_mov_b64 s[10:11], s[0:1]
	ds_read_b128 v[194:197], v0
	ds_read_b128 v[198:201], v0 offset:1024
	ds_read_b128 v[202:205], v0 offset:8192
	ds_read_b128 v[220:223], v0 offset:9216
	ds_read_b128 v[224:227], v2
	ds_read_b128 v[228:231], v2 offset:1024
	ds_read_b128 v[232:235], v2 offset:8192
	ds_read_b128 v[4:7], v2 offset:9216
	ds_read_b128 v[8:11], v3
	ds_read_b128 v[12:15], v3 offset:1024
	ds_read_b128 v[16:19], v3 offset:8192
	ds_read_b128 v[164:167], v3 offset:9216
	s_waitcnt lgkmcnt(8)
	v_mfma_f32_16x16x32_bf16 v[132:135], v[194:197], v[20:23], 0
	v_mfma_f32_16x16x32_bf16 v[140:143], v[198:201], v[20:23], 0
	v_mfma_f32_16x16x32_bf16 v[136:139], v[202:205], v[20:23], 0
	v_mfma_f32_16x16x32_bf16 v[144:147], v[220:223], v[20:23], 0
	ds_read_b128 v[194:197], v168
	ds_read_b128 v[198:201], v168 offset:1024
	ds_read_b128 v[202:205], v168 offset:8192
	ds_read_b128 v[220:223], v168 offset:9216
	s_waitcnt lgkmcnt(8)
	v_mfma_f32_16x16x32_bf16 v[132:135], v[224:227], v[24:27], v[132:135]
	v_mfma_f32_16x16x32_bf16 v[140:143], v[228:231], v[24:27], v[140:143]
	v_mfma_f32_16x16x32_bf16 v[136:139], v[232:235], v[24:27], v[136:139]
	v_mfma_f32_16x16x32_bf16 v[144:147], v[4:7], v[24:27], v[144:147]
	s_waitcnt lgkmcnt(4)
	v_mfma_f32_16x16x32_bf16 v[132:135], v[8:11], v[28:31], v[132:135]
	v_mfma_f32_16x16x32_bf16 v[140:143], v[12:15], v[28:31], v[140:143]
	v_mfma_f32_16x16x32_bf16 v[136:139], v[16:19], v[28:31], v[136:139]
	v_mfma_f32_16x16x32_bf16 v[144:147], v[164:167], v[28:31], v[144:147]
	s_waitcnt lgkmcnt(0)
	v_mfma_f32_16x16x32_bf16 v[132:135], v[194:197], v[32:35], v[132:135]
	v_mfma_f32_16x16x32_bf16 v[140:143], v[198:201], v[32:35], v[140:143]
	v_mfma_f32_16x16x32_bf16 v[136:139], v[202:205], v[32:35], v[136:139]
	v_mfma_f32_16x16x32_bf16 v[144:147], v[220:223], v[32:35], v[144:147]
	s_nop 7
	s_cbranch_vccnz .LBB0_620
	v_cndmask_b32_e64 v4, v244, 0, s[6:7]
	s_mov_b32 s28, 0x3e0293ee
	v_pk_fma_f32 v[164:165], v[134:135], s[28:29], v[4:5] op_sel_hi:[1,0,0]
	v_pk_fma_f32 v[168:169], v[142:143], s[28:29], v[4:5] op_sel_hi:[1,0,0]
	v_pk_fma_f32 v[2:3], v[132:133], s[28:29], v[4:5] op_sel_hi:[1,0,0]
	v_max_f32_e32 v0, v164, v165
	v_pk_fma_f32 v[166:167], v[140:141], s[28:29], v[4:5] op_sel_hi:[1,0,0]
	v_max_f32_e32 v170, v168, v169
	v_max3_f32 v0, v2, v3, v0
	v_max3_f32 v170, v166, v167, v170
	s_mov_b32 s10, 0xff800000
	v_pk_fma_f32 v[172:173], v[138:139], s[28:29], v[4:5] op_sel_hi:[1,0,0]
	v_max3_f32 v0, v0, s10, v170
	v_pk_fma_f32 v[170:171], v[136:137], s[28:29], v[4:5] op_sel_hi:[1,0,0]
	v_max_f32_e32 v174, v172, v173
	v_pk_fma_f32 v[176:177], v[146:147], s[28:29], v[4:5] op_sel_hi:[1,0,0]
	v_max3_f32 v190, v170, v171, v174
	v_pk_fma_f32 v[174:175], v[144:145], s[28:29], v[4:5] op_sel_hi:[1,0,0]
	v_max_f32_e32 v191, v176, v177
	v_max3_f32 v191, v174, v175, v191
	v_max3_f32 v0, v0, v190, v191
	s_mov_b64 s[10:11], 0

; __device__ void moba_item(const P& p, int bh, int qt, char* smem) {
;     ...
;     const int blk = tt >> 2;
;     const bool own = (blk == qblk);
;     const bool rowvalid = own || ((mymask >> blk) & 1u);
;     if (__any(rowvalid)) {
;       const int key0 = tt * 64;
;       f32x4 sacc[2][2];
; #pragma unroll
;       for (int st = 0; st < 2; ++st)
; #pragma unroll
;         for (int kt = 0; kt < 2; ++kt) {
;           sacc[st][kt] = (f32x4){0.f, 0.f, 0.f, 0.f};
;           const int row = 32 * st + 8 * (li >> 2) + 4 * kt + (li & 3);
; #pragma unroll
;           for (int kk = 0; kk < 4; ++kk) {
;             const bf16x8 kf = *(const bf16x8*)(sK + row * 256 + (((kk * 4 + g) ^ li) << 4));
;             sacc[st][kt] = __builtin_amdgcn_mfma_f32_16x16x32_bf16(kf, qf[kk], sacc[st][kt], 0, 0, 0);
;           }
;         }
;       const bool diag = (tt == ntiles - 1);
;       float mx = -INFINITY;
;       if (diag || !__all(rowvalid)) {
; #pragma unroll
;         for (int st = 0; st < 2; ++st)
; #pragma unroll
;           for (int kt = 0; kt < 2; ++kt)
; #pragma unroll
;             for (int r = 0; r < 4; ++r) {
;               const int key = key0 + 32 * st + 8 * g + 4 * kt + r;
;               bool ok = rowvalid && (!diag || key <= qpos);
;               const float sv = ok ? sacc[st][kt][r] * SC : -INFINITY;
;               sacc[st][kt][r] = sv;
;               mx = fmaxf(mx, sv);
;             }
;       } else {
; #pragma unroll
;         for (int st = 0; st < 2; ++st)
; #pragma unroll
;           for (int kt = 0; kt < 2; ++kt) {
;             sacc[st][kt] *= SC;
;             mx = fmaxf(mx, fmaxf(fmaxf(sacc[st][kt][0], sacc[st][kt][1]), fmaxf(sacc[st][kt][2], sacc[st][kt][3])));
;           }
;       }
.Lmoba_skipB:
.LBB0_628:
	v_cndmask_b32_e64 v0, 0, 1, s[6:7]
	v_cmp_ne_u32_e32 vcc, 0, v0
	s_cbranch_vccz .LBB0_612
	v_add_u32_e32 v2, v155, v151
	v_add_u32_e32 v3, v155, v178
	v_add_u32_e32 v168, v155, v179
	v_add_u32_e32 v169, v155, v180
	s_cmp_eq_u32 s24, s27
	s_cselect_b64 s[0:1], -1, 0
	s_and_b64 vcc, exec, s[0:1]
	s_mov_b64 s[10:11], s[0:1]
	ds_read_b128 v[194:197], v2 offset:32768
	ds_read_b128 v[198:201], v2 offset:33792
	ds_read_b128 v[202:205], v2 offset:40960
	ds_read_b128 v[220:223], v2 offset:41984
	ds_read_b128 v[224:227], v3 offset:32768
	ds_read_b128 v[228:231], v3 offset:33792
	ds_read_b128 v[232:235], v3 offset:40960
	ds_read_b128 v[4:7], v3 offset:41984
	ds_read_b128 v[8:11], v168 offset:32768
	ds_read_b128 v[12:15], v168 offset:33792
	ds_read_b128 v[16:19], v168 offset:40960
	ds_read_b128 v[164:167], v168 offset:41984
	s_waitcnt lgkmcnt(8)
	v_mfma_f32_16x16x32_bf16 v[132:135], v[194:197], v[20:23], 0
	v_mfma_f32_16x16x32_bf16 v[140:143], v[198:201], v[20:23], 0
	v_mfma_f32_16x16x32_bf16 v[136:139], v[202:205], v[20:23], 0
	v_mfma_f32_16x16x32_bf16 v[144:147], v[220:223], v[20:23], 0
	ds_read_b128 v[194:197], v169 offset:32768
	ds_read_b128 v[198:201], v169 offset:33792
	ds_read_b128 v[202:205], v169 offset:40960
	ds_read_b128 v[220:223], v169 offset:41984
	s_waitcnt lgkmcnt(8)
	v_mfma_f32_16x16x32_bf16 v[132:135], v[224:227], v[24:27], v[132:135]
	v_mfma_f32_16x16x32_bf16 v[140:143], v[228:231], v[24:27], v[140:143]
	v_mfma_f32_16x16x32_bf16 v[136:139], v[232:235], v[24:27], v[136:139]
	v_mfma_f32_16x16x32_bf16 v[144:147], v[4:7], v[24:27], v[144:147]
	s_waitcnt lgkmcnt(4)
	v_mfma_f32_16x16x32_bf16 v[132:135], v[8:11], v[28:31], v[132:135]
	v_mfma_f32_16x16x32_bf16 v[140:143], v[12:15], v[28:31], v[140:143]
	v_mfma_f32_16x16x32_bf16 v[136:139], v[16:19], v[28:31], v[136:139]
	v_mfma_f32_16x16x32_bf16 v[144:147], v[164:167], v[28:31], v[144:147]
	s_waitcnt lgkmcnt(0)
	v_mfma_f32_16x16x32_bf16 v[132:135], v[194:197], v[32:35], v[132:135]
	v_mfma_f32_16x16x32_bf16 v[140:143], v[198:201], v[32:35], v[140:143]
	v_mfma_f32_16x16x32_bf16 v[136:139], v[202:205], v[32:35], v[136:139]
	v_mfma_f32_16x16x32_bf16 v[144:147], v[220:223], v[32:35], v[144:147]
	s_nop 7
	s_cbranch_vccnz .LBB0_632
	v_cndmask_b32_e64 v4, v244, 0, s[6:7]
	s_mov_b32 s28, 0x3e0293ee
	v_pk_fma_f32 v[164:165], v[134:135], s[28:29], v[4:5] op_sel_hi:[1,0,0]
	v_pk_fma_f32 v[2:3], v[132:133], s[28:29], v[4:5] op_sel_hi:[1,0,0]
	v_max_f32_e32 v166, v164, v165
	v_pk_fma_f32 v[168:169], v[142:143], s[28:29], v[4:5] op_sel_hi:[1,0,0]
	v_max3_f32 v170, v2, v3, v166
	v_pk_fma_f32 v[166:167], v[140:141], s[28:29], v[4:5] op_sel_hi:[1,0,0]
	v_max_f32_e32 v171, v168, v169
	v_max3_f32 v171, v166, v167, v171
	s_mov_b32 s10, 0xff800000
	v_pk_fma_f32 v[172:173], v[138:139], s[28:29], v[4:5] op_sel_hi:[1,0,0]
	v_max3_f32 v189, v170, s10, v171
	v_pk_fma_f32 v[170:171], v[136:137], s[28:29], v[4:5] op_sel_hi:[1,0,0]
	v_max_f32_e32 v174, v172, v173
	v_pk_fma_f32 v[176:177], v[146:147], s[28:29], v[4:5] op_sel_hi:[1,0,0]
	v_max3_f32 v191, v170, v171, v174
	v_pk_fma_f32 v[174:175], v[144:145], s[28:29], v[4:5] op_sel_hi:[1,0,0]
	v_max_f32_e32 v192, v176, v177
	v_max3_f32 v192, v174, v175, v192
	v_max3_f32 v189, v189, v191, v192
	s_mov_b64 s[10:11], 0
